# sequence-DFT phase: Z-chunk global loads (8) and twiddle loads (32) issued ahead into distinct registers with counted vmcnt instead of load->vmcnt(0) per use
# speedup vs baseline: 1.0167x; 1.0167x over previous
.LBB0_1228:
	s_ashr_i32 s7, s6, 31
	s_lshl_b64 s[0:1], s[6:7], 16
	v_lshl_add_u64 v[4:5], v[148:149], 0, s[0:1]
	global_load_dwordx4 v[8:11], v[4:5], off
	v_add_co_u32_e32 v0, vcc, 0x2000, v4
	s_nop 1
	v_addc_co_u32_e32 v1, vcc, 0, v5, vcc
	global_load_dwordx4 v[12:15], v[0:1], off
	v_add_co_u32_e32 v0, vcc, 0x4000, v4
	s_nop 1
	v_addc_co_u32_e32 v1, vcc, 0, v5, vcc
	global_load_dwordx4 v[16:19], v[0:1], off
	v_add_co_u32_e32 v0, vcc, 0x6000, v4
	s_nop 1
	v_addc_co_u32_e32 v1, vcc, 0, v5, vcc
	global_load_dwordx4 v[20:23], v[0:1], off
	v_add_co_u32_e32 v0, vcc, 0x8000, v4
	s_nop 1
	v_addc_co_u32_e32 v1, vcc, 0, v5, vcc
	global_load_dwordx4 v[24:27], v[0:1], off
	v_add_co_u32_e32 v0, vcc, 0xa000, v4
	s_nop 1
	v_addc_co_u32_e32 v1, vcc, 0, v5, vcc
	global_load_dwordx4 v[28:31], v[0:1], off
	v_add_co_u32_e32 v0, vcc, 0xc000, v4
	s_nop 1
	v_addc_co_u32_e32 v1, vcc, 0, v5, vcc
	global_load_dwordx4 v[32:35], v[0:1], off
	v_add_co_u32_e32 v0, vcc, 0xe000, v4
	s_nop 1
	v_addc_co_u32_e32 v1, vcc, 0, v5, vcc
	global_load_dwordx4 v[36:39], v[0:1], off
	s_mov_b64 s[0:1], 0
	v_mov_b32_e32 v169, v155
	s_waitcnt vmcnt(7)
	ds_write_b128 v157, v[8:11]
	s_waitcnt vmcnt(6)
	ds_write_b128 v157, v[12:15] offset:8192
	s_waitcnt vmcnt(5)
	ds_write_b128 v157, v[16:19] offset:16384
	s_waitcnt vmcnt(4)
	ds_write_b128 v157, v[20:23] offset:24576
	s_waitcnt vmcnt(3)
	ds_write_b128 v157, v[24:27] offset:32768
	s_waitcnt vmcnt(2)
	ds_write_b128 v157, v[28:31] offset:40960
	s_waitcnt vmcnt(1)
	ds_write_b128 v157, v[32:35] offset:49152
	s_waitcnt vmcnt(0)
	ds_write_b128 v157, v[36:39] offset:57344
	v_mov_b32_e32 v0, 0
	v_mov_b32_e32 v1, v0
	v_mov_b32_e32 v2, v0
	v_mov_b32_e32 v3, v0
	v_mov_b32_e32 v4, v0
	v_mov_b32_e32 v5, v0
	v_mov_b32_e32 v6, v0
	v_mov_b32_e32 v7, v0
	v_mov_b32_e32 v8, v0
	v_mov_b32_e32 v9, v0
	v_mov_b32_e32 v10, v0
	v_mov_b32_e32 v11, v0
	v_mov_b32_e32 v12, v0
	v_mov_b32_e32 v13, v0
	v_mov_b32_e32 v14, v0
	v_mov_b32_e32 v15, v0
	v_mov_b32_e32 v16, v0
	v_mov_b32_e32 v17, v0
	v_mov_b32_e32 v18, v0
	v_mov_b32_e32 v19, v0
	v_mov_b32_e32 v20, v0
	v_mov_b32_e32 v21, v0
	v_mov_b32_e32 v22, v0
	v_mov_b32_e32 v23, v0
	v_mov_b32_e32 v24, v0
	v_mov_b32_e32 v25, v0
	v_mov_b32_e32 v26, v0
	v_mov_b32_e32 v27, v0
	v_mov_b32_e32 v28, v0
	v_mov_b32_e32 v29, v0
	v_mov_b32_e32 v30, v0
	v_mov_b32_e32 v31, v0
	v_mov_b32_e32 v32, v0
	v_mov_b32_e32 v33, v0
	v_mov_b32_e32 v34, v0
	v_mov_b32_e32 v35, v0
	v_mov_b32_e32 v36, v0
	v_mov_b32_e32 v37, v0
	v_mov_b32_e32 v38, v0
	v_mov_b32_e32 v39, v0
	v_mov_b32_e32 v40, v0
	v_mov_b32_e32 v41, v0
	v_mov_b32_e32 v42, v0
	v_mov_b32_e32 v43, v0
	v_mov_b32_e32 v44, v0
	v_mov_b32_e32 v45, v0
	v_mov_b32_e32 v46, v0
	v_mov_b32_e32 v47, v0
	v_mov_b32_e32 v48, v0
	v_mov_b32_e32 v49, v0
	v_mov_b32_e32 v50, v0
	v_mov_b32_e32 v51, v0
	v_mov_b32_e32 v52, v0
	v_mov_b32_e32 v53, v0
	v_mov_b32_e32 v54, v0
	v_mov_b32_e32 v55, v0
	v_mov_b32_e32 v56, v0
	v_mov_b32_e32 v57, v0
	v_mov_b32_e32 v58, v0
	v_mov_b32_e32 v59, v0
	v_mov_b32_e32 v60, v0
	v_mov_b32_e32 v61, v0
	v_mov_b32_e32 v62, v0
	v_mov_b32_e32 v63, v0
	s_waitcnt lgkmcnt(0)
	s_barrier
.LBB0_1229:
	v_lshl_add_u64 v[152:153], v[150:151], 0, s[0:1]
	v_add_co_u32_e32 v152, vcc, s57, v152
	v_add_u32_e32 v186, 0x400, v169
	s_nop 0
	v_addc_co_u32_e32 v153, vcc, 0, v153, vcc
	global_load_dwordx4 v[170:173], v[152:153], off
	ds_read2_b32 v[182:183], v169 offset1:32
	ds_read2_b32 v[174:175], v169 offset0:128 offset1:160
	ds_read2_b32 v[184:185], v186 offset1:32
	ds_read2_b32 v[176:177], v186 offset0:128 offset1:160
	v_add_u32_e32 v187, 0x1400, v169
	s_add_u32 s0, s0, 0x80
	s_waitcnt lgkmcnt(3)
	v_mov_b32_e32 v178, v182
	s_waitcnt lgkmcnt(2)
	v_mov_b32_e32 v179, v174
	s_waitcnt lgkmcnt(0)
	v_mov_b32_e32 v181, v176
	v_mov_b32_e32 v174, v183
	v_mov_b32_e32 v176, v185
	v_mov_b32_e32 v180, v184
	s_addc_u32 s1, s1, 0
	s_cmpk_lg_i32 s0, 0x200
	s_waitcnt vmcnt(0)
	v_mfma_f32_32x32x16_bf16 v[32:47], v[170:173], v[174:177], v[32:47]
	ds_read2_b32 v[182:183], v169 offset0:64 offset1:96
	ds_read2_b32 v[174:175], v169 offset0:192 offset1:224
	ds_read2_b32 v[184:185], v186 offset0:64 offset1:96
	ds_read2_b32 v[176:177], v186 offset0:192 offset1:224
	v_add_u32_e32 v186, 0x1000, v169
	v_mfma_f32_32x32x16_bf16 v[48:63], v[170:173], v[178:181], v[48:63]
	s_waitcnt lgkmcnt(3)
	v_mov_b32_e32 v178, v182
	s_waitcnt lgkmcnt(2)
	v_mov_b32_e32 v179, v174
	s_waitcnt lgkmcnt(1)
	v_mov_b32_e32 v180, v184
	s_waitcnt lgkmcnt(0)
	v_mov_b32_e32 v181, v176
	v_mov_b32_e32 v174, v183
	v_mov_b32_e32 v176, v185
	v_mfma_f32_32x32x16_bf16 v[16:31], v[170:173], v[178:181], v[16:31]
	s_nop 0
	v_mfma_f32_32x32x16_bf16 v[0:15], v[170:173], v[174:177], v[0:15]
	global_load_dwordx4 v[170:173], v[152:153], off offset:32
	ds_read2_b32 v[182:183], v186 offset1:32
	ds_read2_b32 v[174:175], v186 offset0:128 offset1:160
	ds_read2_b32 v[184:185], v187 offset1:32
	ds_read2_b32 v[176:177], v187 offset0:128 offset1:160
	s_waitcnt lgkmcnt(3)
	v_mov_b32_e32 v178, v182
	s_waitcnt lgkmcnt(2)
	v_mov_b32_e32 v179, v174
	s_waitcnt lgkmcnt(0)
	v_mov_b32_e32 v181, v176
	v_mov_b32_e32 v174, v183
	v_mov_b32_e32 v176, v185
	v_mov_b32_e32 v180, v184
	s_waitcnt vmcnt(0)
	v_mfma_f32_32x32x16_bf16 v[32:47], v[170:173], v[174:177], v[32:47]
	ds_read2_b32 v[182:183], v186 offset0:64 offset1:96
	ds_read2_b32 v[174:175], v186 offset0:192 offset1:224
	ds_read2_b32 v[184:185], v187 offset0:64 offset1:96
	ds_read2_b32 v[176:177], v187 offset0:192 offset1:224
	v_add_u32_e32 v186, 0x2000, v169
	v_add_u32_e32 v187, 0x2400, v169
	v_mfma_f32_32x32x16_bf16 v[48:63], v[170:173], v[178:181], v[48:63]
	s_waitcnt lgkmcnt(3)
	v_mov_b32_e32 v178, v182
	s_waitcnt lgkmcnt(2)
	v_mov_b32_e32 v179, v174
	s_waitcnt lgkmcnt(1)
	v_mov_b32_e32 v180, v184
	s_waitcnt lgkmcnt(0)
	v_mov_b32_e32 v181, v176
	v_mov_b32_e32 v174, v183
	v_mov_b32_e32 v176, v185
	v_mfma_f32_32x32x16_bf16 v[16:31], v[170:173], v[178:181], v[16:31]
	s_nop 0
	v_mfma_f32_32x32x16_bf16 v[0:15], v[170:173], v[174:177], v[0:15]
	global_load_dwordx4 v[170:173], v[152:153], off offset:64
	ds_read2_b32 v[182:183], v186 offset1:32
	ds_read2_b32 v[174:175], v186 offset0:128 offset1:160
	ds_read2_b32 v[184:185], v187 offset1:32
	ds_read2_b32 v[176:177], v187 offset0:128 offset1:160
	s_waitcnt lgkmcnt(3)
	v_mov_b32_e32 v178, v182
	s_waitcnt lgkmcnt(2)
	v_mov_b32_e32 v179, v174
	s_waitcnt lgkmcnt(0)
	v_mov_b32_e32 v181, v176
	v_mov_b32_e32 v174, v183
	v_mov_b32_e32 v176, v185
	v_mov_b32_e32 v180, v184
	s_waitcnt vmcnt(0)
	v_mfma_f32_32x32x16_bf16 v[32:47], v[170:173], v[174:177], v[32:47]
	ds_read2_b32 v[182:183], v186 offset0:64 offset1:96
	ds_read2_b32 v[174:175], v186 offset0:192 offset1:224
	ds_read2_b32 v[184:185], v187 offset0:64 offset1:96
	ds_read2_b32 v[176:177], v187 offset0:192 offset1:224
	v_mfma_f32_32x32x16_bf16 v[48:63], v[170:173], v[178:181], v[48:63]
	s_waitcnt lgkmcnt(3)
	v_mov_b32_e32 v178, v182
	s_waitcnt lgkmcnt(2)
	v_mov_b32_e32 v179, v174
	s_waitcnt lgkmcnt(1)
	v_mov_b32_e32 v180, v184
	s_waitcnt lgkmcnt(0)
	v_mov_b32_e32 v181, v176
	v_mov_b32_e32 v174, v183
	v_mov_b32_e32 v176, v185
	v_add_u32_e32 v184, 0x3000, v169
	v_mfma_f32_32x32x16_bf16 v[16:31], v[170:173], v[178:181], v[16:31]
	v_add_u32_e32 v185, 0x3400, v169
	v_add_u32_e32 v169, 0x4000, v169
	v_mfma_f32_32x32x16_bf16 v[0:15], v[170:173], v[174:177], v[0:15]
	global_load_dwordx4 v[170:173], v[152:153], off offset:96
	ds_read2_b32 v[152:153], v184 offset1:32
	ds_read2_b32 v[174:175], v184 offset0:128 offset1:160
	ds_read2_b32 v[182:183], v185 offset1:32
	ds_read2_b32 v[176:177], v185 offset0:128 offset1:160
	s_waitcnt lgkmcnt(3)
	v_mov_b32_e32 v178, v152
	s_waitcnt lgkmcnt(2)
	v_mov_b32_e32 v179, v174
	s_waitcnt lgkmcnt(0)
	v_mov_b32_e32 v181, v176
	v_mov_b32_e32 v174, v153
	v_mov_b32_e32 v176, v183
	v_mov_b32_e32 v180, v182
	s_waitcnt vmcnt(0)
	v_mfma_f32_32x32x16_bf16 v[32:47], v[170:173], v[174:177], v[32:47]
	ds_read2_b32 v[152:153], v184 offset0:64 offset1:96
	ds_read2_b32 v[174:175], v184 offset0:192 offset1:224
	ds_read2_b32 v[182:183], v185 offset0:64 offset1:96
	ds_read2_b32 v[176:177], v185 offset0:192 offset1:224
	v_mfma_f32_32x32x16_bf16 v[48:63], v[170:173], v[178:181], v[48:63]
	s_waitcnt lgkmcnt(3)
	v_mov_b32_e32 v178, v152
	s_waitcnt lgkmcnt(2)
	v_mov_b32_e32 v179, v174
	s_waitcnt lgkmcnt(1)
	v_mov_b32_e32 v180, v182
	s_waitcnt lgkmcnt(0)
	v_mov_b32_e32 v181, v176
	v_mov_b32_e32 v174, v153
	v_mov_b32_e32 v176, v183
	v_mfma_f32_32x32x16_bf16 v[16:31], v[170:173], v[178:181], v[16:31]
	s_nop 0
	v_mfma_f32_32x32x16_bf16 v[0:15], v[170:173], v[174:177], v[0:15]
	s_cbranch_scc1 .LBB0_1229
	global_load_dwordx2 v[188:189], v[66:67], off
	global_load_dwordx2 v[190:191], v[68:69], off
	global_load_dwordx2 v[192:193], v[70:71], off
	global_load_dwordx2 v[194:195], v[72:73], off
	global_load_dwordx2 v[196:197], v[74:75], off
	global_load_dwordx2 v[198:199], v[76:77], off
	global_load_dwordx2 v[200:201], v[78:79], off
	global_load_dwordx2 v[202:203], v[80:81], off
	global_load_dwordx2 v[204:205], v[82:83], off
	global_load_dwordx2 v[206:207], v[84:85], off
	global_load_dwordx2 v[224:225], v[86:87], off
	global_load_dwordx2 v[226:227], v[88:89], off
	global_load_dwordx2 v[228:229], v[90:91], off
	global_load_dwordx2 v[230:231], v[92:93], off
	global_load_dwordx2 v[232:233], v[94:95], off
	global_load_dwordx2 v[234:235], v[96:97], off
	s_mov_b64 s[0:1], s[8:9]
	s_lshl_b32 s4, s6, 5
	s_lshl_b32 s5, s6, 2
	s_and_b32 s4, s4, 0xffffe000
	s_and_b32 s5, s5, 0x3fc
	s_waitcnt vmcnt(15)
	v_mul_f32_e32 v169, v49, v189
	v_fmac_f32_e32 v169, v48, v188
	v_mul_f32_e32 v48, v48, v189
	v_fma_f32 v48, v49, v188, -v48
	v_bfe_u32 v49, v169, 16, 1
	v_add3_u32 v49, v169, v49, s94
	v_bfe_u32 v152, v48, 16, 1
	v_lshrrev_b32_e32 v49, 16, v49
	v_add3_u32 v48, v48, v152, s94
	v_and_or_b32 v48, v48, s86, v49
	v_add_u32_e32 v49, v156, v158
	ds_write_b32 v49, v48
	global_load_dwordx2 v[188:189], v[98:99], off
	s_waitcnt vmcnt(15)
	v_mul_f32_e32 v152, v51, v191
	v_fmac_f32_e32 v152, v50, v190
	v_mul_f32_e32 v49, v50, v191
	v_fma_f32 v48, v51, v190, -v49
	v_bfe_u32 v49, v152, 16, 1
	v_add3_u32 v49, v152, v49, s94
	v_bfe_u32 v50, v48, 16, 1
	v_lshrrev_b32_e32 v49, 16, v49
	v_add3_u32 v48, v48, v50, s94
	v_and_or_b32 v48, v48, s86, v49
	v_add_u32_e32 v49, v156, v159
	ds_write_b32 v49, v48
	global_load_dwordx2 v[190:191], v[100:101], off
	s_waitcnt vmcnt(15)
	v_mul_f32_e32 v50, v53, v193
	v_fmac_f32_e32 v50, v52, v192
	v_mul_f32_e32 v49, v52, v193
	v_fma_f32 v48, v53, v192, -v49
	v_bfe_u32 v49, v50, 16, 1
	v_add3_u32 v49, v50, v49, s94
	v_bfe_u32 v50, v48, 16, 1
	v_lshrrev_b32_e32 v49, 16, v49
	v_add3_u32 v48, v48, v50, s94
	v_and_or_b32 v48, v48, s86, v49
	v_add_u32_e32 v49, v156, v160
	ds_write_b32 v49, v48
	global_load_dwordx2 v[192:193], v[102:103], off
	s_waitcnt vmcnt(15)
	v_mul_f32_e32 v50, v55, v195
	v_fmac_f32_e32 v50, v54, v194
	v_mul_f32_e32 v49, v54, v195
	v_fma_f32 v48, v55, v194, -v49
	v_bfe_u32 v49, v50, 16, 1
	v_add3_u32 v49, v50, v49, s94
	v_bfe_u32 v50, v48, 16, 1
	v_lshrrev_b32_e32 v49, 16, v49
	v_add3_u32 v48, v48, v50, s94
	v_and_or_b32 v48, v48, s86, v49
	v_add_u32_e32 v49, v156, v161
	ds_write_b32 v49, v48
	global_load_dwordx2 v[194:195], v[104:105], off
	s_waitcnt vmcnt(15)
	v_mul_f32_e32 v50, v57, v197
	v_fmac_f32_e32 v50, v56, v196
	v_mul_f32_e32 v49, v56, v197
	v_fma_f32 v48, v57, v196, -v49
	v_bfe_u32 v49, v50, 16, 1
	v_add3_u32 v49, v50, v49, s94
	v_bfe_u32 v50, v48, 16, 1
	v_lshrrev_b32_e32 v49, 16, v49
	v_add3_u32 v48, v48, v50, s94
	v_and_or_b32 v48, v48, s86, v49
	v_add_u32_e32 v49, v156, v162
	ds_write_b32 v49, v48
	global_load_dwordx2 v[196:197], v[106:107], off
	s_waitcnt vmcnt(15)
	v_mul_f32_e32 v50, v59, v199
	v_fmac_f32_e32 v50, v58, v198
	v_mul_f32_e32 v49, v58, v199
	v_fma_f32 v48, v59, v198, -v49
	v_bfe_u32 v49, v50, 16, 1
	v_add3_u32 v49, v50, v49, s94
	v_bfe_u32 v50, v48, 16, 1
	v_lshrrev_b32_e32 v49, 16, v49
	v_add3_u32 v48, v48, v50, s94
	v_and_or_b32 v48, v48, s86, v49
	v_add_u32_e32 v49, v156, v163
	ds_write_b32 v49, v48
	global_load_dwordx2 v[198:199], v[108:109], off
	s_waitcnt vmcnt(15)
	v_mul_f32_e32 v50, v61, v201
	v_fmac_f32_e32 v50, v60, v200
	v_mul_f32_e32 v49, v60, v201
	v_fma_f32 v48, v61, v200, -v49
	v_bfe_u32 v49, v50, 16, 1
	v_add3_u32 v49, v50, v49, s94
	v_bfe_u32 v50, v48, 16, 1
	v_lshrrev_b32_e32 v49, 16, v49
	v_add3_u32 v48, v48, v50, s94
	v_and_or_b32 v48, v48, s86, v49
	v_add_u32_e32 v49, v156, v164
	ds_write_b32 v49, v48
	global_load_dwordx2 v[200:201], v[110:111], off
	s_waitcnt vmcnt(15)
	v_mul_f32_e32 v50, v63, v203
	v_fmac_f32_e32 v50, v62, v202
	v_mul_f32_e32 v49, v62, v203
	v_fma_f32 v48, v63, v202, -v49
	v_bfe_u32 v49, v50, 16, 1
	v_add3_u32 v49, v50, v49, s94
	v_bfe_u32 v50, v48, 16, 1
	v_lshrrev_b32_e32 v49, 16, v49
	v_add3_u32 v48, v48, v50, s94
	v_and_or_b32 v48, v48, s86, v49
	v_add_u32_e32 v49, v156, v165
	ds_write_b32 v49, v48
	global_load_dwordx2 v[202:203], v[112:113], off
	s_waitcnt vmcnt(15)
	v_mul_f32_e32 v50, v33, v205
	v_fmac_f32_e32 v50, v32, v204
	v_mul_f32_e32 v32, v32, v205
	v_fma_f32 v32, v33, v204, -v32
	v_bfe_u32 v33, v50, 16, 1
	v_add3_u32 v33, v50, v33, s94
	v_bfe_u32 v48, v32, 16, 1
	v_lshrrev_b32_e32 v33, 16, v33
	v_add3_u32 v32, v32, v48, s94
	v_and_or_b32 v32, v32, s86, v33
	v_add_u32_e32 v33, v166, v158
	ds_write_b32 v33, v32
	global_load_dwordx2 v[204:205], v[114:115], off
	s_waitcnt vmcnt(15)
	v_mul_f32_e32 v48, v35, v207
	v_fmac_f32_e32 v48, v34, v206
	v_mul_f32_e32 v33, v34, v207
	v_fma_f32 v32, v35, v206, -v33
	v_bfe_u32 v33, v48, 16, 1
	v_add3_u32 v33, v48, v33, s94
	v_bfe_u32 v34, v32, 16, 1
	v_lshrrev_b32_e32 v33, 16, v33
	v_add3_u32 v32, v32, v34, s94
	v_and_or_b32 v32, v32, s86, v33
	v_add_u32_e32 v33, v166, v159
	ds_write_b32 v33, v32
	global_load_dwordx2 v[206:207], v[116:117], off
	s_waitcnt vmcnt(15)
	v_mul_f32_e32 v34, v37, v225
	v_fmac_f32_e32 v34, v36, v224
	v_mul_f32_e32 v33, v36, v225
	v_fma_f32 v32, v37, v224, -v33
	v_bfe_u32 v33, v34, 16, 1
	v_add3_u32 v33, v34, v33, s94
	v_bfe_u32 v34, v32, 16, 1
	v_lshrrev_b32_e32 v33, 16, v33
	v_add3_u32 v32, v32, v34, s94
	v_and_or_b32 v32, v32, s86, v33
	v_add_u32_e32 v33, v166, v160
	ds_write_b32 v33, v32
	global_load_dwordx2 v[224:225], v[118:119], off
	s_waitcnt vmcnt(15)
	v_mul_f32_e32 v34, v39, v227
	v_fmac_f32_e32 v34, v38, v226
	v_mul_f32_e32 v33, v38, v227
	v_fma_f32 v32, v39, v226, -v33
	v_bfe_u32 v33, v34, 16, 1
	v_add3_u32 v33, v34, v33, s94
	v_bfe_u32 v34, v32, 16, 1
	v_lshrrev_b32_e32 v33, 16, v33
	v_add3_u32 v32, v32, v34, s94
	v_and_or_b32 v32, v32, s86, v33
	v_add_u32_e32 v33, v166, v161
	ds_write_b32 v33, v32
	global_load_dwordx2 v[226:227], v[120:121], off
	s_waitcnt vmcnt(15)
	v_mul_f32_e32 v34, v41, v229
	v_fmac_f32_e32 v34, v40, v228
	v_mul_f32_e32 v33, v40, v229
	v_fma_f32 v32, v41, v228, -v33
	v_bfe_u32 v33, v34, 16, 1
	v_add3_u32 v33, v34, v33, s94
	v_bfe_u32 v34, v32, 16, 1
	v_lshrrev_b32_e32 v33, 16, v33
	v_add3_u32 v32, v32, v34, s94
	v_and_or_b32 v32, v32, s86, v33
	v_add_u32_e32 v33, v166, v162
	ds_write_b32 v33, v32
	global_load_dwordx2 v[228:229], v[122:123], off
	s_waitcnt vmcnt(15)
	v_mul_f32_e32 v34, v43, v231
	v_fmac_f32_e32 v34, v42, v230
	v_mul_f32_e32 v33, v42, v231
	v_fma_f32 v32, v43, v230, -v33
	v_bfe_u32 v33, v34, 16, 1
	v_add3_u32 v33, v34, v33, s94
	v_bfe_u32 v34, v32, 16, 1
	v_lshrrev_b32_e32 v33, 16, v33
	v_add3_u32 v32, v32, v34, s94
	v_and_or_b32 v32, v32, s86, v33
	v_add_u32_e32 v33, v166, v163
	ds_write_b32 v33, v32
	global_load_dwordx2 v[230:231], v[124:125], off
	s_waitcnt vmcnt(15)
	v_mul_f32_e32 v34, v45, v233
	v_fmac_f32_e32 v34, v44, v232
	v_mul_f32_e32 v33, v44, v233
	v_fma_f32 v32, v45, v232, -v33
	v_bfe_u32 v33, v34, 16, 1
	v_add3_u32 v33, v34, v33, s94
	v_bfe_u32 v34, v32, 16, 1
	v_lshrrev_b32_e32 v33, 16, v33
	v_add3_u32 v32, v32, v34, s94
	v_and_or_b32 v32, v32, s86, v33
	v_add_u32_e32 v33, v166, v164
	ds_write_b32 v33, v32
	global_load_dwordx2 v[232:233], v[126:127], off
	s_waitcnt vmcnt(15)
	v_mul_f32_e32 v34, v47, v235
	v_fmac_f32_e32 v34, v46, v234
	v_mul_f32_e32 v33, v46, v235
	v_fma_f32 v32, v47, v234, -v33
	v_bfe_u32 v33, v34, 16, 1
	v_add3_u32 v33, v34, v33, s94
	v_bfe_u32 v34, v32, 16, 1
	v_lshrrev_b32_e32 v33, 16, v33
	v_add3_u32 v32, v32, v34, s94
	v_and_or_b32 v32, v32, s86, v33
	v_add_u32_e32 v33, v166, v165
	ds_write_b32 v33, v32
	global_load_dwordx2 v[234:235], v[128:129], off
	s_waitcnt vmcnt(15)
	v_mul_f32_e32 v34, v17, v189
	v_fmac_f32_e32 v34, v16, v188
	v_mul_f32_e32 v16, v16, v189
	v_fma_f32 v16, v17, v188, -v16
	v_bfe_u32 v17, v34, 16, 1
	v_add3_u32 v17, v34, v17, s94
	v_bfe_u32 v32, v16, 16, 1
	v_lshrrev_b32_e32 v17, 16, v17
	v_add3_u32 v16, v16, v32, s94
	v_and_or_b32 v16, v16, s86, v17
	v_add_u32_e32 v17, v167, v158
	ds_write_b32 v17, v16
	s_waitcnt vmcnt(14)
	v_mul_f32_e32 v32, v19, v191
	v_fmac_f32_e32 v32, v18, v190
	v_mul_f32_e32 v17, v18, v191
	v_fma_f32 v16, v19, v190, -v17
	v_bfe_u32 v17, v32, 16, 1
	v_add3_u32 v17, v32, v17, s94
	v_bfe_u32 v18, v16, 16, 1
	v_lshrrev_b32_e32 v17, 16, v17
	v_add3_u32 v16, v16, v18, s94
	v_and_or_b32 v16, v16, s86, v17
	v_add_u32_e32 v17, v167, v159
	ds_write_b32 v17, v16
	s_waitcnt vmcnt(13)
	v_mul_f32_e32 v18, v21, v193
	v_fmac_f32_e32 v18, v20, v192
	v_mul_f32_e32 v17, v20, v193
	v_fma_f32 v16, v21, v192, -v17
	v_bfe_u32 v17, v18, 16, 1
	v_add3_u32 v17, v18, v17, s94
	v_bfe_u32 v18, v16, 16, 1
	v_lshrrev_b32_e32 v17, 16, v17
	v_add3_u32 v16, v16, v18, s94
	v_and_or_b32 v16, v16, s86, v17
	v_add_u32_e32 v17, v167, v160
	ds_write_b32 v17, v16
	s_waitcnt vmcnt(12)
	v_mul_f32_e32 v18, v23, v195
	v_fmac_f32_e32 v18, v22, v194
	v_mul_f32_e32 v17, v22, v195
	v_fma_f32 v16, v23, v194, -v17
	v_bfe_u32 v17, v18, 16, 1
	v_add3_u32 v17, v18, v17, s94
	v_bfe_u32 v18, v16, 16, 1
	v_lshrrev_b32_e32 v17, 16, v17
	v_add3_u32 v16, v16, v18, s94
	v_and_or_b32 v16, v16, s86, v17
	v_add_u32_e32 v17, v167, v161
	ds_write_b32 v17, v16
	s_waitcnt vmcnt(11)
	v_mul_f32_e32 v18, v25, v197
	v_fmac_f32_e32 v18, v24, v196
	v_mul_f32_e32 v17, v24, v197
	v_fma_f32 v16, v25, v196, -v17
	v_bfe_u32 v17, v18, 16, 1
	v_add3_u32 v17, v18, v17, s94
	v_bfe_u32 v18, v16, 16, 1
	v_lshrrev_b32_e32 v17, 16, v17
	v_add3_u32 v16, v16, v18, s94
	v_and_or_b32 v16, v16, s86, v17
	v_add_u32_e32 v17, v167, v162
	ds_write_b32 v17, v16
	s_waitcnt vmcnt(10)
	v_mul_f32_e32 v18, v27, v199
	v_fmac_f32_e32 v18, v26, v198
	v_mul_f32_e32 v17, v26, v199
	v_fma_f32 v16, v27, v198, -v17
	v_bfe_u32 v17, v18, 16, 1
	v_add3_u32 v17, v18, v17, s94
	v_bfe_u32 v18, v16, 16, 1
	v_lshrrev_b32_e32 v17, 16, v17
	v_add3_u32 v16, v16, v18, s94
	v_and_or_b32 v16, v16, s86, v17
	v_add_u32_e32 v17, v167, v163
	ds_write_b32 v17, v16
	s_waitcnt vmcnt(9)
	v_mul_f32_e32 v18, v29, v201
	v_fmac_f32_e32 v18, v28, v200
	v_mul_f32_e32 v17, v28, v201
	v_fma_f32 v16, v29, v200, -v17
	v_bfe_u32 v17, v18, 16, 1
	v_add3_u32 v17, v18, v17, s94
	v_bfe_u32 v18, v16, 16, 1
	v_lshrrev_b32_e32 v17, 16, v17
	v_add3_u32 v16, v16, v18, s94
	v_and_or_b32 v16, v16, s86, v17
	v_add_u32_e32 v17, v167, v164
	ds_write_b32 v17, v16
	s_waitcnt vmcnt(8)
	v_mul_f32_e32 v18, v31, v203
	v_fmac_f32_e32 v18, v30, v202
	v_mul_f32_e32 v17, v30, v203
	v_fma_f32 v16, v31, v202, -v17
	v_bfe_u32 v17, v18, 16, 1
	v_add3_u32 v17, v18, v17, s94
	v_bfe_u32 v18, v16, 16, 1
	v_lshrrev_b32_e32 v17, 16, v17
	v_add3_u32 v16, v16, v18, s94
	v_and_or_b32 v16, v16, s86, v17
	v_add_u32_e32 v17, v167, v165
	ds_write_b32 v17, v16
	s_waitcnt vmcnt(7)
	v_mul_f32_e32 v18, v1, v205
	v_fmac_f32_e32 v18, v0, v204
	v_mul_f32_e32 v0, v0, v205
	v_fma_f32 v0, v1, v204, -v0
	v_bfe_u32 v1, v18, 16, 1
	v_add3_u32 v1, v18, v1, s94
	v_bfe_u32 v16, v0, 16, 1
	v_lshrrev_b32_e32 v1, 16, v1
	v_add3_u32 v0, v0, v16, s94
	v_and_or_b32 v0, v0, s86, v1
	v_add_u32_e32 v1, v168, v158
	ds_write_b32 v1, v0
	s_waitcnt vmcnt(6)
	v_mul_f32_e32 v16, v3, v207
	v_fmac_f32_e32 v16, v2, v206
	v_mul_f32_e32 v1, v2, v207
	v_fma_f32 v0, v3, v206, -v1
	v_bfe_u32 v1, v16, 16, 1
	v_add3_u32 v1, v16, v1, s94
	v_bfe_u32 v2, v0, 16, 1
	v_lshrrev_b32_e32 v1, 16, v1
	v_add3_u32 v0, v0, v2, s94
	v_and_or_b32 v0, v0, s86, v1
	v_add_u32_e32 v1, v168, v159
	ds_write_b32 v1, v0
	s_waitcnt vmcnt(5)
	v_mul_f32_e32 v2, v5, v225
	v_fmac_f32_e32 v2, v4, v224
	v_mul_f32_e32 v1, v4, v225
	v_fma_f32 v0, v5, v224, -v1
	v_bfe_u32 v1, v2, 16, 1
	v_add3_u32 v1, v2, v1, s94
	v_bfe_u32 v2, v0, 16, 1
	v_lshrrev_b32_e32 v1, 16, v1
	v_add3_u32 v0, v0, v2, s94
	v_and_or_b32 v0, v0, s86, v1
	v_add_u32_e32 v1, v168, v160
	ds_write_b32 v1, v0
	s_waitcnt vmcnt(4)
	v_mul_f32_e32 v2, v7, v227
	v_fmac_f32_e32 v2, v6, v226
	v_mul_f32_e32 v1, v6, v227
	v_fma_f32 v0, v7, v226, -v1
	v_bfe_u32 v1, v2, 16, 1
	v_add3_u32 v1, v2, v1, s94
	v_bfe_u32 v2, v0, 16, 1
	v_lshrrev_b32_e32 v1, 16, v1
	v_add3_u32 v0, v0, v2, s94
	v_and_or_b32 v0, v0, s86, v1
	v_add_u32_e32 v1, v168, v161
	ds_write_b32 v1, v0
	s_waitcnt vmcnt(3)
	v_mul_f32_e32 v2, v9, v229
	v_fmac_f32_e32 v2, v8, v228
	v_mul_f32_e32 v1, v8, v229
	v_fma_f32 v0, v9, v228, -v1
	v_bfe_u32 v1, v2, 16, 1
	v_add3_u32 v1, v2, v1, s94
	v_bfe_u32 v2, v0, 16, 1
	v_lshrrev_b32_e32 v1, 16, v1
	v_add3_u32 v0, v0, v2, s94
	v_and_or_b32 v0, v0, s86, v1
	v_add_u32_e32 v1, v168, v162
	ds_write_b32 v1, v0
	s_waitcnt vmcnt(2)
	v_mul_f32_e32 v2, v11, v231
	v_fmac_f32_e32 v2, v10, v230
	v_mul_f32_e32 v1, v10, v231
	v_fma_f32 v0, v11, v230, -v1
	v_bfe_u32 v1, v2, 16, 1
	v_add3_u32 v1, v2, v1, s94
	v_bfe_u32 v2, v0, 16, 1
	v_lshrrev_b32_e32 v1, 16, v1
	v_add3_u32 v0, v0, v2, s94
	v_and_or_b32 v0, v0, s86, v1
	v_add_u32_e32 v1, v168, v163
	ds_write_b32 v1, v0
	s_waitcnt vmcnt(1)
	v_mul_f32_e32 v2, v13, v233
	v_fmac_f32_e32 v2, v12, v232
	v_mul_f32_e32 v1, v12, v233
	v_fma_f32 v0, v13, v232, -v1
	v_bfe_u32 v1, v2, 16, 1
	v_add3_u32 v1, v2, v1, s94
	v_bfe_u32 v2, v0, 16, 1
	v_lshrrev_b32_e32 v1, 16, v1
	v_add3_u32 v0, v0, v2, s94
	v_and_or_b32 v0, v0, s86, v1
	v_add_u32_e32 v1, v168, v164
	ds_write_b32 v1, v0
	s_waitcnt vmcnt(0)
	v_mul_f32_e32 v2, v15, v235
	v_fmac_f32_e32 v2, v14, v234
	v_mul_f32_e32 v1, v14, v235
	v_fma_f32 v0, v15, v234, -v1
	v_bfe_u32 v1, v2, 16, 1
	v_add3_u32 v1, v2, v1, s94
	v_bfe_u32 v2, v0, 16, 1
	v_lshrrev_b32_e32 v1, 16, v1
	v_add3_u32 v0, v0, v2, s94
	v_and_or_b32 v0, v0, s86, v1
	v_add_u32_e32 v1, v168, v165
	ds_write_b32 v1, v0
	s_waitcnt lgkmcnt(0)
	s_barrier
	global_load_dwordx4 v[0:3], v[130:131], off
	ds_read_b128 v[4:7], v65
	ds_read_b128 v[32:35], v65 offset:32
	s_waitcnt vmcnt(0) lgkmcnt(1)
	v_mfma_f32_32x32x16_bf16 v[16:31], v[0:3], v[4:7], 0
	global_load_dwordx4 v[0:3], v[132:133], off
	global_load_dwordx4 v[36:39], v[130:131], off offset:32
	s_waitcnt vmcnt(0) lgkmcnt(0)
	v_mfma_f32_32x32x16_bf16 v[16:31], v[36:39], v[32:35], v[16:31]
	global_load_dwordx4 v[36:39], v[134:135], off
	v_mfma_f32_32x32x16_bf16 v[0:15], v[0:3], v[4:7], 0
	s_waitcnt vmcnt(0)
	v_mfma_f32_32x32x16_bf16 v[0:15], v[36:39], v[32:35], v[0:15]
	global_load_dwordx4 v[36:39], v[130:131], off offset:64
	ds_read_b128 v[32:35], v65 offset:64
	s_waitcnt vmcnt(0) lgkmcnt(0)
	v_mfma_f32_32x32x16_bf16 v[16:31], v[36:39], v[32:35], v[16:31]
	global_load_dwordx4 v[36:39], v[136:137], off
	s_waitcnt vmcnt(0)
	v_mfma_f32_32x32x16_bf16 v[0:15], v[36:39], v[32:35], v[0:15]
	global_load_dwordx4 v[36:39], v[130:131], off offset:96
	ds_read_b128 v[32:35], v65 offset:96
	s_waitcnt vmcnt(0) lgkmcnt(0)
	v_mfma_f32_32x32x16_bf16 v[16:31], v[36:39], v[32:35], v[16:31]
	global_load_dwordx4 v[36:39], v[138:139], off
	s_waitcnt vmcnt(0)
	v_mfma_f32_32x32x16_bf16 v[0:15], v[36:39], v[32:35], v[0:15]
	global_load_dwordx4 v[36:39], v[130:131], off offset:128
	ds_read_b128 v[32:35], v65 offset:128
	s_waitcnt vmcnt(0) lgkmcnt(0)
	v_mfma_f32_32x32x16_bf16 v[16:31], v[36:39], v[32:35], v[16:31]
	global_load_dwordx4 v[36:39], v[140:141], off
	s_waitcnt vmcnt(0)
	v_mfma_f32_32x32x16_bf16 v[0:15], v[36:39], v[32:35], v[0:15]
	global_load_dwordx4 v[36:39], v[130:131], off offset:160
	ds_read_b128 v[32:35], v65 offset:160
	s_waitcnt vmcnt(0) lgkmcnt(0)
	v_mfma_f32_32x32x16_bf16 v[16:31], v[36:39], v[32:35], v[16:31]
	global_load_dwordx4 v[36:39], v[142:143], off
	s_waitcnt vmcnt(0)
	v_mfma_f32_32x32x16_bf16 v[0:15], v[36:39], v[32:35], v[0:15]
	global_load_dwordx4 v[36:39], v[130:131], off offset:192
	ds_read_b128 v[32:35], v65 offset:192
	s_waitcnt vmcnt(0) lgkmcnt(0)
	v_mfma_f32_32x32x16_bf16 v[16:31], v[36:39], v[32:35], v[16:31]
	global_load_dwordx4 v[36:39], v[144:145], off
	s_waitcnt vmcnt(0)
	v_mfma_f32_32x32x16_bf16 v[0:15], v[36:39], v[32:35], v[0:15]
	global_load_dwordx4 v[36:39], v[130:131], off offset:224
	ds_read_b128 v[32:35], v65 offset:224
	s_waitcnt vmcnt(0) lgkmcnt(0)
	v_mfma_f32_32x32x16_bf16 v[16:31], v[36:39], v[32:35], v[16:31]
	global_load_dwordx4 v[36:39], v[146:147], off
	s_nop 10
	v_mul_f32_e32 v16, 0x3a800000, v16
	s_waitcnt vmcnt(0)
	v_mfma_f32_32x32x16_bf16 v[0:15], v[36:39], v[32:35], v[0:15]
	v_mov_b32_e32 v34, v154
	s_add_u32 s0, s0, s5
	v_and_or_b32 v32, v34, 30, s12
	v_ashrrev_i32_e32 v35, 1, v32
	v_and_b32_e32 v32, 1, v34
	v_lshlrev_b32_e32 v34, 4, v34
	v_and_b32_e32 v34, 0xfffffe00, v34
	s_addc_u32 s1, s1, 0
	v_lshlrev_b32_e32 v208, 1, v32
	v_add3_u32 v34, v35, s4, v34
	v_lshl_add_u64 v[32:33], s[0:1], 0, v[208:209]
	s_mov_b64 s[0:1], 0xf900000
	v_bfe_u32 v36, v16, 16, 1
	v_ashrrev_i32_e32 v35, 31, v34
	v_lshl_add_u64 v[32:33], v[32:33], 0, s[0:1]
	v_add3_u32 v16, v16, v36, s94
	v_lshlrev_b64 v[36:37], 10, v[34:35]
	v_lshl_add_u64 v[36:37], v[32:33], 0, v[36:37]
	flat_store_short_d16_hi v[36:37], v16
	v_mul_f32_e32 v16, 0x3a800000, v17
	v_bfe_u32 v17, v16, 16, 1
	v_add3_u32 v35, v16, v17, s94
	v_add_u32_e32 v16, 0x80, v34
	v_ashrrev_i32_e32 v17, 31, v16
	v_lshlrev_b64 v[16:17], 10, v[16:17]
	v_lshl_add_u64 v[16:17], v[32:33], 0, v[16:17]
	flat_store_short_d16_hi v[16:17], v35
	v_mul_f32_e32 v16, 0x3a800000, v18
	v_bfe_u32 v17, v16, 16, 1
	v_add3_u32 v18, v16, v17, s94
	v_add_u32_e32 v16, 0x100, v34
	v_ashrrev_i32_e32 v17, 31, v16
	v_lshlrev_b64 v[16:17], 10, v[16:17]
	v_lshl_add_u64 v[16:17], v[32:33], 0, v[16:17]
	flat_store_short_d16_hi v[16:17], v18
	v_mul_f32_e32 v16, 0x3a800000, v19
	v_bfe_u32 v17, v16, 16, 1
	v_add3_u32 v18, v16, v17, s94
	v_add_u32_e32 v16, 0x180, v34
	v_ashrrev_i32_e32 v17, 31, v16
	v_lshlrev_b64 v[16:17], 10, v[16:17]
	v_lshl_add_u64 v[16:17], v[32:33], 0, v[16:17]
	flat_store_short_d16_hi v[16:17], v18
	v_mul_f32_e32 v16, 0x3a800000, v20
	v_bfe_u32 v17, v16, 16, 1
	v_add3_u32 v18, v16, v17, s94
	v_add_u32_e32 v16, 0x400, v34
	v_ashrrev_i32_e32 v17, 31, v16
	v_lshlrev_b64 v[16:17], 10, v[16:17]
	v_lshl_add_u64 v[16:17], v[32:33], 0, v[16:17]
	flat_store_short_d16_hi v[16:17], v18
	v_mul_f32_e32 v16, 0x3a800000, v21
	v_bfe_u32 v17, v16, 16, 1
	v_add3_u32 v18, v16, v17, s94
	v_add_u32_e32 v16, 0x480, v34
	v_ashrrev_i32_e32 v17, 31, v16
	v_lshlrev_b64 v[16:17], 10, v[16:17]
	v_lshl_add_u64 v[16:17], v[32:33], 0, v[16:17]
	flat_store_short_d16_hi v[16:17], v18
	v_mul_f32_e32 v16, 0x3a800000, v22
	v_bfe_u32 v17, v16, 16, 1
	v_add3_u32 v18, v16, v17, s94
	v_add_u32_e32 v16, 0x500, v34
	v_ashrrev_i32_e32 v17, 31, v16
	v_lshlrev_b64 v[16:17], 10, v[16:17]
	v_lshl_add_u64 v[16:17], v[32:33], 0, v[16:17]
	flat_store_short_d16_hi v[16:17], v18
	v_mul_f32_e32 v16, 0x3a800000, v23
	v_bfe_u32 v17, v16, 16, 1
	v_add3_u32 v18, v16, v17, s94
	v_add_u32_e32 v16, 0x580, v34
	v_ashrrev_i32_e32 v17, 31, v16
	v_lshlrev_b64 v[16:17], 10, v[16:17]
	v_lshl_add_u64 v[16:17], v[32:33], 0, v[16:17]
	flat_store_short_d16_hi v[16:17], v18
	v_mul_f32_e32 v16, 0x3a800000, v24
	v_bfe_u32 v17, v16, 16, 1
	v_add3_u32 v18, v16, v17, s94
	v_add_u32_e32 v16, 0x800, v34
	v_ashrrev_i32_e32 v17, 31, v16
	v_lshlrev_b64 v[16:17], 10, v[16:17]
	v_lshl_add_u64 v[16:17], v[32:33], 0, v[16:17]
	flat_store_short_d16_hi v[16:17], v18
	v_mul_f32_e32 v16, 0x3a800000, v25
	v_bfe_u32 v17, v16, 16, 1
	v_add3_u32 v18, v16, v17, s94
	v_add_u32_e32 v16, 0x880, v34
	v_ashrrev_i32_e32 v17, 31, v16
	v_lshlrev_b64 v[16:17], 10, v[16:17]
	v_lshl_add_u64 v[16:17], v[32:33], 0, v[16:17]
	flat_store_short_d16_hi v[16:17], v18
	v_mul_f32_e32 v16, 0x3a800000, v26
	v_bfe_u32 v17, v16, 16, 1
	v_add3_u32 v18, v16, v17, s94
	v_add_u32_e32 v16, 0x900, v34
	v_ashrrev_i32_e32 v17, 31, v16
	v_lshlrev_b64 v[16:17], 10, v[16:17]
	v_lshl_add_u64 v[16:17], v[32:33], 0, v[16:17]
	flat_store_short_d16_hi v[16:17], v18
	v_mul_f32_e32 v16, 0x3a800000, v27
	v_bfe_u32 v17, v16, 16, 1
	v_add3_u32 v18, v16, v17, s94
	v_add_u32_e32 v16, 0x980, v34
	v_ashrrev_i32_e32 v17, 31, v16
	v_lshlrev_b64 v[16:17], 10, v[16:17]
	v_lshl_add_u64 v[16:17], v[32:33], 0, v[16:17]
	flat_store_short_d16_hi v[16:17], v18
	v_mul_f32_e32 v16, 0x3a800000, v28
	v_bfe_u32 v17, v16, 16, 1
	v_add3_u32 v18, v16, v17, s94
	v_add_u32_e32 v16, 0xc00, v34
	v_ashrrev_i32_e32 v17, 31, v16
	v_lshlrev_b64 v[16:17], 10, v[16:17]
	v_lshl_add_u64 v[16:17], v[32:33], 0, v[16:17]
	flat_store_short_d16_hi v[16:17], v18
	v_mul_f32_e32 v16, 0x3a800000, v29
	v_bfe_u32 v17, v16, 16, 1
	v_add3_u32 v18, v16, v17, s94
	v_add_u32_e32 v16, 0xc80, v34
	v_ashrrev_i32_e32 v17, 31, v16
	v_lshlrev_b64 v[16:17], 10, v[16:17]
	v_lshl_add_u64 v[16:17], v[32:33], 0, v[16:17]
	flat_store_short_d16_hi v[16:17], v18
	v_mul_f32_e32 v16, 0x3a800000, v30
	v_bfe_u32 v17, v16, 16, 1
	v_add3_u32 v18, v16, v17, s94
	v_add_u32_e32 v16, 0xd00, v34
	v_ashrrev_i32_e32 v17, 31, v16
	v_lshlrev_b64 v[16:17], 10, v[16:17]
	v_lshl_add_u64 v[16:17], v[32:33], 0, v[16:17]
	flat_store_short_d16_hi v[16:17], v18
	v_mul_f32_e32 v16, 0x3a800000, v31
	v_bfe_u32 v17, v16, 16, 1
	v_add3_u32 v18, v16, v17, s94
	v_add_u32_e32 v16, 0xd80, v34
	v_ashrrev_i32_e32 v17, 31, v16
	v_lshlrev_b64 v[16:17], 10, v[16:17]
	v_lshl_add_u64 v[16:17], v[32:33], 0, v[16:17]
	v_mul_f32_e32 v0, 0x3a800000, v0
	flat_store_short_d16_hi v[16:17], v18
	v_bfe_u32 v16, v0, 16, 1
	v_add3_u32 v0, v0, v16, s94
	v_add_u32_e32 v16, 0x1000, v34
	v_ashrrev_i32_e32 v17, 31, v16
	v_lshlrev_b64 v[16:17], 10, v[16:17]
	v_lshl_add_u64 v[16:17], v[32:33], 0, v[16:17]
	flat_store_short_d16_hi v[16:17], v0
	v_mul_f32_e32 v0, 0x3a800000, v1
	v_bfe_u32 v1, v0, 16, 1
	v_add3_u32 v16, v0, v1, s94
	v_add_u32_e32 v0, 0x1080, v34
	v_ashrrev_i32_e32 v1, 31, v0
	v_lshlrev_b64 v[0:1], 10, v[0:1]
	v_lshl_add_u64 v[0:1], v[32:33], 0, v[0:1]
	flat_store_short_d16_hi v[0:1], v16
	v_mul_f32_e32 v0, 0x3a800000, v2
	v_bfe_u32 v1, v0, 16, 1
	v_add3_u32 v2, v0, v1, s94
	v_add_u32_e32 v0, 0x1100, v34
	v_ashrrev_i32_e32 v1, 31, v0
	v_lshlrev_b64 v[0:1], 10, v[0:1]
	v_lshl_add_u64 v[0:1], v[32:33], 0, v[0:1]
	flat_store_short_d16_hi v[0:1], v2
	v_mul_f32_e32 v0, 0x3a800000, v3
	v_bfe_u32 v1, v0, 16, 1
	v_add3_u32 v2, v0, v1, s94
	v_add_u32_e32 v0, 0x1180, v34
	v_ashrrev_i32_e32 v1, 31, v0
	v_lshlrev_b64 v[0:1], 10, v[0:1]
	v_lshl_add_u64 v[0:1], v[32:33], 0, v[0:1]
	flat_store_short_d16_hi v[0:1], v2
	v_mul_f32_e32 v0, 0x3a800000, v4
	v_bfe_u32 v1, v0, 16, 1
	v_add3_u32 v2, v0, v1, s94
	v_add_u32_e32 v0, 0x1400, v34
	v_ashrrev_i32_e32 v1, 31, v0
	v_lshlrev_b64 v[0:1], 10, v[0:1]
	v_lshl_add_u64 v[0:1], v[32:33], 0, v[0:1]
	flat_store_short_d16_hi v[0:1], v2
	v_mul_f32_e32 v0, 0x3a800000, v5
	v_bfe_u32 v1, v0, 16, 1
	v_add3_u32 v2, v0, v1, s94
	v_add_u32_e32 v0, 0x1480, v34
	v_ashrrev_i32_e32 v1, 31, v0
	v_lshlrev_b64 v[0:1], 10, v[0:1]
	v_lshl_add_u64 v[0:1], v[32:33], 0, v[0:1]
	flat_store_short_d16_hi v[0:1], v2
	v_mul_f32_e32 v0, 0x3a800000, v6
	v_bfe_u32 v1, v0, 16, 1
	v_add3_u32 v2, v0, v1, s94
	v_add_u32_e32 v0, 0x1500, v34
	v_ashrrev_i32_e32 v1, 31, v0
	v_lshlrev_b64 v[0:1], 10, v[0:1]
	v_lshl_add_u64 v[0:1], v[32:33], 0, v[0:1]
	flat_store_short_d16_hi v[0:1], v2
	v_mul_f32_e32 v0, 0x3a800000, v7
	v_bfe_u32 v1, v0, 16, 1
	v_add3_u32 v2, v0, v1, s94
	v_add_u32_e32 v0, 0x1580, v34
	v_ashrrev_i32_e32 v1, 31, v0
	v_lshlrev_b64 v[0:1], 10, v[0:1]
	v_lshl_add_u64 v[0:1], v[32:33], 0, v[0:1]
	flat_store_short_d16_hi v[0:1], v2
	v_mul_f32_e32 v0, 0x3a800000, v8
	v_bfe_u32 v1, v0, 16, 1
	v_add3_u32 v2, v0, v1, s94
	v_add_u32_e32 v0, 0x1800, v34
	v_ashrrev_i32_e32 v1, 31, v0
	v_lshlrev_b64 v[0:1], 10, v[0:1]
	v_lshl_add_u64 v[0:1], v[32:33], 0, v[0:1]
	flat_store_short_d16_hi v[0:1], v2
	v_mul_f32_e32 v0, 0x3a800000, v9
	v_bfe_u32 v1, v0, 16, 1
	v_add3_u32 v2, v0, v1, s94
	v_add_u32_e32 v0, 0x1880, v34
	v_ashrrev_i32_e32 v1, 31, v0
	v_lshlrev_b64 v[0:1], 10, v[0:1]
	v_lshl_add_u64 v[0:1], v[32:33], 0, v[0:1]
	flat_store_short_d16_hi v[0:1], v2
	v_mul_f32_e32 v0, 0x3a800000, v10
	v_bfe_u32 v1, v0, 16, 1
	v_add3_u32 v2, v0, v1, s94
	v_add_u32_e32 v0, 0x1900, v34
	v_ashrrev_i32_e32 v1, 31, v0
	v_lshlrev_b64 v[0:1], 10, v[0:1]
	v_lshl_add_u64 v[0:1], v[32:33], 0, v[0:1]
	flat_store_short_d16_hi v[0:1], v2
	v_mul_f32_e32 v0, 0x3a800000, v11
	v_bfe_u32 v1, v0, 16, 1
	v_add3_u32 v2, v0, v1, s94
	v_add_u32_e32 v0, 0x1980, v34
	v_ashrrev_i32_e32 v1, 31, v0
	v_lshlrev_b64 v[0:1], 10, v[0:1]
	v_lshl_add_u64 v[0:1], v[32:33], 0, v[0:1]
	flat_store_short_d16_hi v[0:1], v2
	v_mul_f32_e32 v0, 0x3a800000, v12
	v_bfe_u32 v1, v0, 16, 1
	v_add3_u32 v2, v0, v1, s94
	v_add_u32_e32 v0, 0x1c00, v34
	v_ashrrev_i32_e32 v1, 31, v0
	v_lshlrev_b64 v[0:1], 10, v[0:1]
	v_lshl_add_u64 v[0:1], v[32:33], 0, v[0:1]
	flat_store_short_d16_hi v[0:1], v2
	v_mul_f32_e32 v0, 0x3a800000, v13
	v_bfe_u32 v1, v0, 16, 1
	v_add3_u32 v2, v0, v1, s94
	v_add_u32_e32 v0, 0x1c80, v34
	v_ashrrev_i32_e32 v1, 31, v0
	v_lshlrev_b64 v[0:1], 10, v[0:1]
	v_lshl_add_u64 v[0:1], v[32:33], 0, v[0:1]
	flat_store_short_d16_hi v[0:1], v2
	v_mul_f32_e32 v0, 0x3a800000, v14
	v_bfe_u32 v1, v0, 16, 1
	v_add3_u32 v2, v0, v1, s94
	v_add_u32_e32 v0, 0x1d00, v34
	v_ashrrev_i32_e32 v1, 31, v0
	v_lshlrev_b64 v[0:1], 10, v[0:1]
	v_lshl_add_u64 v[0:1], v[32:33], 0, v[0:1]
	flat_store_short_d16_hi v[0:1], v2
	v_mul_f32_e32 v0, 0x3a800000, v15
	v_bfe_u32 v1, v0, 16, 1
	v_add3_u32 v2, v0, v1, s94
	v_add_u32_e32 v0, 0x1d80, v34
	v_ashrrev_i32_e32 v1, 31, v0
	v_lshlrev_b64 v[0:1], 10, v[0:1]
	s_add_i32 s6, s6, s52
	v_lshl_add_u64 v[0:1], v[32:33], 0, v[0:1]
	s_cmpk_lt_i32 s6, 0x200
	flat_store_short_d16_hi v[0:1], v2
	s_waitcnt lgkmcnt(0)
	s_barrier
	s_cbranch_scc1 .LBB0_1228
